# Y branch-GEMM b-even epilogue: second half's gate bytes prefetched together with the first half (one round trip instead of three); GLA-prep counted wait
# baseline (speedup 1.0000x reference)
.LBB0_744:
	v_lshl_add_u64 v[4:5], s[82:83], 0, v[26:27]
	v_add_co_u32_e32 v6, vcc, 0x2000, v4
	s_nop 4
	v_cvt_pk_bf16_f32 v0, v0, s0
	v_addc_co_u32_e32 v7, vcc, 0, v5, vcc
	global_store_short v[6:7], v0, off offset:1024
	v_add_co_u32_e32 v0, vcc, 0x5000, v4
	v_cvt_pk_bf16_f32 v6, v1, s0
	s_nop 0
	v_addc_co_u32_e32 v1, vcc, 0, v5, vcc
	global_store_short v[0:1], v6, off offset:3072
	v_add_co_u32_e32 v0, vcc, 0x9000, v4
	v_cvt_pk_bf16_f32 v2, v2, s0
	s_nop 0
	v_addc_co_u32_e32 v1, vcc, 0, v5, vcc
	global_store_short v[0:1], v2, off offset:1024
	v_lshl_add_u64 v[0:1], s[34:35], 0, v[24:25]
	v_add_co_u32_e32 v0, vcc, 0xffeef000, v0
	v_cvt_pk_bf16_f32 v2, v3, s0
	s_nop 0
	v_addc_co_u32_e32 v1, vcc, -1, v1, vcc
	global_store_short v[0:1], v2, off offset:-3072
	s_waitcnt lgkmcnt(0)
	s_barrier
	s_add_i32 s20, s20, -1
	s_mov_b64 s[10:11], 0x300
	s_waitcnt vmcnt(19)
	v_perm_b32 v70, v100, v101, s19
	v_perm_b32 v73, v102, v103, s19
	v_perm_b32 v72, v104, v105, s19
	v_perm_b32 v74, v106, v107, s19
	v_perm_b32 v75, v108, v109, s19
	v_perm_b32 v9, v110, v111, s19
	v_perm_b32 v71, v112, v113, s19
	v_perm_b32 v11, v114, v115, s19
	v_perm_b32 v12, v116, v117, s19
	v_perm_b32 v13, v118, v119, s19
	v_perm_b32 v14, v120, v121, s19
	v_perm_b32 v15, v122, v123, s19
	v_perm_b32 v10, v124, v125, s19
	v_perm_b32 v8, v126, v127, s19
	v_perm_b32 v68, v128, v129, s19
	v_perm_b32 v69, v130, v131, s19
	v_mov_b64_e32 v[0:1], v[8:9]
	v_lshl_add_u64 v[18:19], v[18:19], 0, s[10:11]
	v_lshl_add_u64 v[20:21], v[20:21], 0, s[36:37]
	v_lshl_add_u64 v[22:23], v[22:23], 0, s[36:37]
	v_lshl_add_u64 v[24:25], v[24:25], 0, s[36:37]
	v_lshl_add_u64 v[26:27], v[26:27], 0, s[36:37]
	v_lshl_add_u64 v[28:29], v[28:29], 0, s[36:37]
	v_lshl_add_u64 v[30:31], v[30:31], 0, s[36:37]
	v_lshl_add_u64 v[32:33], v[32:33], 0, s[36:37]
	v_lshl_add_u64 v[34:35], v[34:35], 0, s[36:37]
	v_lshl_add_u64 v[36:37], v[36:37], 0, s[36:37]
	s_cmp_eq_u32 s20, 0
	v_mov_b64_e32 v[2:3], v[10:11]
	v_mov_b64_e32 v[4:5], v[12:13]
	v_mov_b64_e32 v[6:7], v[14:15]
	v_mov_b32_e32 v46, v68
	v_mov_b32_e32 v45, v69
	v_mov_b32_e32 v44, v70
	v_mov_b32_e32 v43, v71
	v_mov_b32_e32 v42, v72
	v_mov_b32_e32 v41, v73
	v_mov_b32_e32 v40, v74
	v_mov_b32_e32 v38, v75
	s_cbranch_scc1 .LBB0_755

.LBB0_1287:
	v_readlane_b32 s12, v252, 34
	v_readlane_b32 s13, v252, 35
	s_add_u32 s12, s12, s22
	s_addc_u32 s13, s13, s23
	v_lshl_add_u64 v[134:135], s[12:13], 0, v[176:177]
	v_lshlrev_b64 v[132:133], 12, v[18:19]
	v_lshl_add_u64 v[132:133], v[134:135], 0, v[132:133]
	global_load_dwordx2 v[160:161], v[132:133], off
	global_load_dwordx2 v[162:163], v[132:133], off offset:1024
	global_load_dwordx2 v[156:157], v[132:133], off offset:128
	global_load_dwordx2 v[158:159], v[132:133], off offset:1152
	v_or_b32_e32 v136, 16, v18
	v_ashrrev_i32_e32 v137, 31, v136
	v_lshlrev_b64 v[136:137], 12, v[136:137]
	v_lshl_add_u64 v[136:137], v[134:135], 0, v[136:137]
	global_load_dwordx2 v[152:153], v[136:137], off
	global_load_dwordx2 v[154:155], v[136:137], off offset:1024
	global_load_dwordx2 v[146:147], v[136:137], off offset:128
	global_load_dwordx2 v[150:151], v[136:137], off offset:1152
	v_or_b32_e32 v136, 32, v18
	v_ashrrev_i32_e32 v137, 31, v136
	v_lshlrev_b64 v[136:137], 12, v[136:137]
	v_lshl_add_u64 v[138:139], v[134:135], 0, v[136:137]
	global_load_dwordx2 v[144:145], v[138:139], off
	global_load_dwordx2 v[148:149], v[138:139], off offset:1024
	global_load_dwordx2 v[136:137], v[138:139], off offset:128
	global_load_dwordx2 v[140:141], v[138:139], off offset:1152
	v_or_b32_e32 v18, 48, v18
	v_ashrrev_i32_e32 v19, 31, v18
	v_lshlrev_b64 v[18:19], 12, v[18:19]
	v_lshl_add_u64 v[134:135], v[134:135], 0, v[18:19]
	global_load_dwordx2 v[138:139], v[134:135], off
	global_load_dwordx2 v[142:143], v[134:135], off offset:1024
	global_load_dwordx2 v[18:19], v[134:135], off offset:128
	s_nop 0
	global_load_dwordx2 v[134:135], v[134:135], off offset:1152
	s_mov_b64 s[12:13], 0x80000
	v_lshl_add_u64 v[226:227], v[132:133], 0, s[12:13]
	global_load_dwordx2 v[194:195], v[226:227], off
	global_load_dwordx2 v[196:197], v[226:227], off offset:1024
	global_load_dwordx2 v[198:199], v[226:227], off offset:128
	global_load_dwordx2 v[200:201], v[226:227], off offset:1152
	s_mov_b64 s[12:13], 0x90000
	v_lshl_add_u64 v[226:227], v[132:133], 0, s[12:13]
	global_load_dwordx2 v[202:203], v[226:227], off
	global_load_dwordx2 v[204:205], v[226:227], off offset:1024
	global_load_dwordx2 v[206:207], v[226:227], off offset:128
	global_load_dwordx2 v[208:209], v[226:227], off offset:1152
	s_mov_b64 s[12:13], 0xa0000
	v_lshl_add_u64 v[226:227], v[132:133], 0, s[12:13]
	global_load_dwordx2 v[210:211], v[226:227], off
	global_load_dwordx2 v[212:213], v[226:227], off offset:1024
	global_load_dwordx2 v[214:215], v[226:227], off offset:128
	global_load_dwordx2 v[216:217], v[226:227], off offset:1152
	s_mov_b64 s[12:13], 0xb0000
	v_lshl_add_u64 v[226:227], v[132:133], 0, s[12:13]
	global_load_dwordx2 v[218:219], v[226:227], off
	global_load_dwordx2 v[220:221], v[226:227], off offset:1024
	global_load_dwordx2 v[222:223], v[226:227], off offset:128
	global_load_dwordx2 v[224:225], v[226:227], off offset:1152
	s_mov_b64 s[12:13], 0x80000
	s_waitcnt vmcnt(0)
	v_cvt_f32_ubyte3_e32 v191, v160
	v_cvt_f32_ubyte1_e32 v176, v162
	v_cvt_f32_ubyte0_e32 v16, v162
	v_mul_f32_e32 v177, 0x3b808081, v176
	v_cvt_f32_ubyte2_e32 v176, v162
	v_cvt_f32_ubyte3_e32 v162, v162
	v_mul_f32_e32 v179, 0x3b808081, v162
	v_cvt_f32_ubyte0_e32 v162, v163
	v_mul_f32_e32 v178, 0x3b808081, v176
	v_mul_f32_e32 v176, 0x3b808081, v162
	v_cvt_f32_ubyte1_e32 v162, v163
	v_mul_f32_e32 v180, 0x3b808081, v162
	v_cvt_f32_ubyte2_e32 v162, v163
	v_mul_f32_e32 v16, 0x3b808081, v16
	v_mul_f32_e32 v181, 0x3b808081, v162
	v_cvt_f32_ubyte3_e32 v162, v163
	v_rcp_f32_e32 v178, v178
	v_rcp_f32_e32 v179, v179
	v_mul_f32_e32 v192, 0x3b808081, v162
	v_rcp_f32_e32 v162, v16
	v_rcp_f32_e32 v163, v177
	v_cvt_f32_ubyte2_e32 v190, v160
	v_rcp_f32_e32 v177, v180
	v_rcp_f32_e32 v180, v181
	v_cvt_f32_ubyte1_e32 v189, v160
	v_cvt_f32_ubyte0_e32 v188, v160
	v_pk_mul_f32 v[190:191], v[190:191], s[30:31] op_sel_hi:[1,0]
	v_rcp_f32_e32 v181, v192
	v_pk_mul_f32 v[188:189], v[188:189], s[30:31] op_sel_hi:[1,0]
	v_pk_mul_f32 v[178:179], v[190:191], v[178:179]
	v_rcp_f32_e32 v176, v176
	v_pk_mul_f32 v[162:163], v[188:189], v[162:163]
	v_pk_mul_f32 v[2:3], v[2:3], v[178:179]
	v_cvt_f32_ubyte3_e32 v179, v161
	v_cvt_f32_ubyte2_e32 v178, v161
	v_pk_mul_f32 v[0:1], v[0:1], v[162:163]
	v_cvt_f32_ubyte1_e32 v163, v161
	v_cvt_f32_ubyte0_e32 v162, v161
	v_pk_mul_f32 v[160:161], v[178:179], s[30:31] op_sel_hi:[1,0]
	v_pk_mul_f32 v[162:163], v[162:163], s[30:31] op_sel_hi:[1,0]
	v_pk_mul_f32 v[160:161], v[160:161], v[180:181]
	v_pk_mul_f32 v[162:163], v[162:163], v[176:177]
	v_pk_mul_f32 v[6:7], v[6:7], v[160:161]
	v_cvt_f32_ubyte1_e32 v160, v158
	v_cvt_f32_ubyte0_e32 v16, v158
	v_mul_f32_e32 v161, 0x3b808081, v160
	v_cvt_f32_ubyte2_e32 v160, v158
	v_cvt_f32_ubyte3_e32 v158, v158
	v_pk_mul_f32 v[4:5], v[4:5], v[162:163]
	v_mul_f32_e32 v163, 0x3b808081, v158
	v_cvt_f32_ubyte0_e32 v158, v159
	v_mul_f32_e32 v162, 0x3b808081, v160
	v_mul_f32_e32 v160, 0x3b808081, v158
	v_cvt_f32_ubyte1_e32 v158, v159
	v_mul_f32_e32 v176, 0x3b808081, v158
	v_cvt_f32_ubyte2_e32 v158, v159
	v_mul_f32_e32 v16, 0x3b808081, v16
	v_mul_f32_e32 v177, 0x3b808081, v158
	v_cvt_f32_ubyte3_e32 v158, v159
	v_rcp_f32_e32 v162, v162
	v_rcp_f32_e32 v163, v163
	v_mul_f32_e32 v188, 0x3b808081, v158
	v_rcp_f32_e32 v158, v16
	v_rcp_f32_e32 v159, v161
	v_cvt_f32_ubyte3_e32 v181, v156
	v_cvt_f32_ubyte2_e32 v180, v156
	v_rcp_f32_e32 v161, v176
	v_rcp_f32_e32 v176, v177
	v_cvt_f32_ubyte1_e32 v179, v156
	v_cvt_f32_ubyte0_e32 v178, v156
	v_pk_mul_f32 v[180:181], v[180:181], s[30:31] op_sel_hi:[1,0]
	v_rcp_f32_e32 v177, v188
	v_pk_mul_f32 v[178:179], v[178:179], s[30:31] op_sel_hi:[1,0]
	v_pk_mul_f32 v[162:163], v[180:181], v[162:163]
	v_rcp_f32_e32 v160, v160
	v_pk_mul_f32 v[158:159], v[178:179], v[158:159]
	v_pk_mul_f32 v[38:39], v[38:39], v[162:163]
	v_cvt_f32_ubyte3_e32 v163, v157
	v_cvt_f32_ubyte2_e32 v162, v157
	v_pk_mul_f32 v[36:37], v[36:37], v[158:159]
	v_cvt_f32_ubyte1_e32 v159, v157
	v_cvt_f32_ubyte0_e32 v158, v157
	v_pk_mul_f32 v[156:157], v[162:163], s[30:31] op_sel_hi:[1,0]
	v_pk_mul_f32 v[158:159], v[158:159], s[30:31] op_sel_hi:[1,0]
	v_pk_mul_f32 v[156:157], v[156:157], v[176:177]
	v_pk_mul_f32 v[158:159], v[158:159], v[160:161]
	v_pk_mul_f32 v[42:43], v[42:43], v[156:157]
	v_cvt_f32_ubyte1_e32 v156, v154
	v_cvt_f32_ubyte0_e32 v16, v154
	v_mul_f32_e32 v157, 0x3b808081, v156
	v_cvt_f32_ubyte2_e32 v156, v154
	v_cvt_f32_ubyte3_e32 v154, v154
	v_pk_mul_f32 v[40:41], v[40:41], v[158:159]
	v_mul_f32_e32 v159, 0x3b808081, v154
	v_cvt_f32_ubyte0_e32 v154, v155
	v_mul_f32_e32 v158, 0x3b808081, v156
	v_mul_f32_e32 v156, 0x3b808081, v154
	v_cvt_f32_ubyte1_e32 v154, v155
	v_mul_f32_e32 v160, 0x3b808081, v154
	v_cvt_f32_ubyte2_e32 v154, v155
	v_mul_f32_e32 v16, 0x3b808081, v16
	v_mul_f32_e32 v161, 0x3b808081, v154
	v_cvt_f32_ubyte3_e32 v154, v155
	v_rcp_f32_e32 v158, v158
	v_rcp_f32_e32 v159, v159
	v_mul_f32_e32 v178, 0x3b808081, v154
	v_rcp_f32_e32 v154, v16
	v_rcp_f32_e32 v155, v157
	v_cvt_f32_ubyte3_e32 v177, v152
	v_cvt_f32_ubyte2_e32 v176, v152
	v_rcp_f32_e32 v157, v160
	v_rcp_f32_e32 v160, v161
	v_cvt_f32_ubyte1_e32 v163, v152
	v_cvt_f32_ubyte0_e32 v162, v152
	v_pk_mul_f32 v[176:177], v[176:177], s[30:31] op_sel_hi:[1,0]
	v_rcp_f32_e32 v161, v178
	v_pk_mul_f32 v[162:163], v[162:163], s[30:31] op_sel_hi:[1,0]
	v_pk_mul_f32 v[158:159], v[176:177], v[158:159]
	v_rcp_f32_e32 v156, v156
	v_pk_mul_f32 v[154:155], v[162:163], v[154:155]
	v_pk_mul_f32 v[10:11], v[10:11], v[158:159]
	v_cvt_f32_ubyte3_e32 v159, v153
	v_cvt_f32_ubyte2_e32 v158, v153
	v_pk_mul_f32 v[8:9], v[8:9], v[154:155]
	v_cvt_f32_ubyte1_e32 v155, v153
	v_cvt_f32_ubyte0_e32 v154, v153
	v_pk_mul_f32 v[152:153], v[158:159], s[30:31] op_sel_hi:[1,0]
	v_pk_mul_f32 v[154:155], v[154:155], s[30:31] op_sel_hi:[1,0]
	v_pk_mul_f32 v[152:153], v[152:153], v[160:161]
	v_pk_mul_f32 v[154:155], v[154:155], v[156:157]
	v_pk_mul_f32 v[14:15], v[14:15], v[152:153]
	v_cvt_f32_ubyte1_e32 v152, v150
	v_cvt_f32_ubyte0_e32 v16, v150
	v_mul_f32_e32 v153, 0x3b808081, v152
	v_cvt_f32_ubyte2_e32 v152, v150
	v_cvt_f32_ubyte3_e32 v150, v150
	v_pk_mul_f32 v[12:13], v[12:13], v[154:155]
	v_mul_f32_e32 v155, 0x3b808081, v150
	v_cvt_f32_ubyte0_e32 v150, v151
	v_mul_f32_e32 v154, 0x3b808081, v152
	v_mul_f32_e32 v152, 0x3b808081, v150
	v_cvt_f32_ubyte1_e32 v150, v151
	v_mul_f32_e32 v156, 0x3b808081, v150
	v_cvt_f32_ubyte2_e32 v150, v151
	v_mul_f32_e32 v16, 0x3b808081, v16
	v_mul_f32_e32 v157, 0x3b808081, v150
	v_cvt_f32_ubyte3_e32 v150, v151
	v_rcp_f32_e32 v154, v154
	v_rcp_f32_e32 v155, v155
	v_mul_f32_e32 v162, 0x3b808081, v150
	v_rcp_f32_e32 v150, v16
	v_rcp_f32_e32 v151, v153
	v_cvt_f32_ubyte3_e32 v161, v146
	v_cvt_f32_ubyte2_e32 v160, v146
	v_rcp_f32_e32 v153, v156
	v_rcp_f32_e32 v156, v157
	v_cvt_f32_ubyte1_e32 v159, v146
	v_cvt_f32_ubyte0_e32 v158, v146
	v_pk_mul_f32 v[160:161], v[160:161], s[30:31] op_sel_hi:[1,0]
	v_rcp_f32_e32 v157, v162
	v_pk_mul_f32 v[158:159], v[158:159], s[30:31] op_sel_hi:[1,0]
	v_pk_mul_f32 v[154:155], v[160:161], v[154:155]
	v_rcp_f32_e32 v152, v152
	v_pk_mul_f32 v[150:151], v[158:159], v[150:151]
	v_pk_mul_f32 v[46:47], v[46:47], v[154:155]
	v_cvt_f32_ubyte3_e32 v155, v147
	v_cvt_f32_ubyte2_e32 v154, v147
	v_pk_mul_f32 v[44:45], v[44:45], v[150:151]
	v_cvt_f32_ubyte1_e32 v151, v147
	v_cvt_f32_ubyte0_e32 v150, v147
	v_pk_mul_f32 v[146:147], v[154:155], s[30:31] op_sel_hi:[1,0]
	v_pk_mul_f32 v[150:151], v[150:151], s[30:31] op_sel_hi:[1,0]
	v_pk_mul_f32 v[146:147], v[146:147], v[156:157]
	v_pk_mul_f32 v[150:151], v[150:151], v[152:153]
	v_pk_mul_f32 v[50:51], v[50:51], v[146:147]
	v_cvt_f32_ubyte1_e32 v146, v148
	v_mul_f32_e32 v147, 0x3b808081, v146
	v_cvt_f32_ubyte2_e32 v146, v148
	v_pk_mul_f32 v[48:49], v[48:49], v[150:151]
	v_mul_f32_e32 v150, 0x3b808081, v146
	v_cvt_f32_ubyte3_e32 v146, v148
	v_mul_f32_e32 v151, 0x3b808081, v146
	v_cvt_f32_ubyte0_e32 v146, v149
	v_cvt_f32_ubyte0_e32 v16, v148
	v_mul_f32_e32 v148, 0x3b808081, v146
	v_cvt_f32_ubyte1_e32 v146, v149
	v_mul_f32_e32 v152, 0x3b808081, v146
	v_cvt_f32_ubyte2_e32 v146, v149
	v_mul_f32_e32 v16, 0x3b808081, v16
	v_mul_f32_e32 v153, 0x3b808081, v146
	v_cvt_f32_ubyte3_e32 v146, v149
	v_rcp_f32_e32 v150, v150
	v_rcp_f32_e32 v151, v151
	v_mul_f32_e32 v158, 0x3b808081, v146
	v_rcp_f32_e32 v146, v16
	v_rcp_f32_e32 v147, v147
	v_cvt_f32_ubyte3_e32 v157, v144
	v_cvt_f32_ubyte2_e32 v156, v144
	v_rcp_f32_e32 v149, v152
	v_rcp_f32_e32 v152, v153
	v_cvt_f32_ubyte1_e32 v155, v144
	v_cvt_f32_ubyte0_e32 v154, v144
	v_pk_mul_f32 v[156:157], v[156:157], s[30:31] op_sel_hi:[1,0]
	v_rcp_f32_e32 v153, v158
	v_pk_mul_f32 v[154:155], v[154:155], s[30:31] op_sel_hi:[1,0]
	v_pk_mul_f32 v[150:151], v[156:157], v[150:151]
	v_rcp_f32_e32 v148, v148
	v_pk_mul_f32 v[146:147], v[154:155], v[146:147]
	v_pk_mul_f32 v[22:23], v[22:23], v[150:151]
	v_cvt_f32_ubyte3_e32 v151, v145
	v_cvt_f32_ubyte2_e32 v150, v145
	v_pk_mul_f32 v[20:21], v[20:21], v[146:147]
	v_cvt_f32_ubyte1_e32 v147, v145
	v_cvt_f32_ubyte0_e32 v146, v145
	v_pk_mul_f32 v[144:145], v[150:151], s[30:31] op_sel_hi:[1,0]
	v_pk_mul_f32 v[146:147], v[146:147], s[30:31] op_sel_hi:[1,0]
	v_pk_mul_f32 v[144:145], v[144:145], v[152:153]
	v_pk_mul_f32 v[146:147], v[146:147], v[148:149]
	v_pk_mul_f32 v[26:27], v[26:27], v[144:145]
	v_cvt_f32_ubyte1_e32 v144, v140
	v_cvt_f32_ubyte0_e32 v16, v140
	v_mul_f32_e32 v145, 0x3b808081, v144
	v_cvt_f32_ubyte2_e32 v144, v140
	v_cvt_f32_ubyte3_e32 v140, v140
	v_pk_mul_f32 v[24:25], v[24:25], v[146:147]
	v_mul_f32_e32 v147, 0x3b808081, v140
	v_cvt_f32_ubyte0_e32 v140, v141
	v_mul_f32_e32 v146, 0x3b808081, v144
	v_mul_f32_e32 v144, 0x3b808081, v140
	v_cvt_f32_ubyte1_e32 v140, v141
	v_mul_f32_e32 v148, 0x3b808081, v140
	v_cvt_f32_ubyte2_e32 v140, v141
	v_mul_f32_e32 v16, 0x3b808081, v16
	v_mul_f32_e32 v149, 0x3b808081, v140
	v_cvt_f32_ubyte3_e32 v140, v141
	v_rcp_f32_e32 v146, v146
	v_rcp_f32_e32 v147, v147
	v_mul_f32_e32 v154, 0x3b808081, v140
	v_rcp_f32_e32 v140, v16
	v_rcp_f32_e32 v141, v145
	v_cvt_f32_ubyte3_e32 v153, v136
	v_cvt_f32_ubyte2_e32 v152, v136
	v_rcp_f32_e32 v145, v148
	v_rcp_f32_e32 v148, v149
	v_cvt_f32_ubyte1_e32 v151, v136
	v_cvt_f32_ubyte0_e32 v150, v136
	v_pk_mul_f32 v[152:153], v[152:153], s[30:31] op_sel_hi:[1,0]
	v_rcp_f32_e32 v149, v154
	v_pk_mul_f32 v[150:151], v[150:151], s[30:31] op_sel_hi:[1,0]
	v_pk_mul_f32 v[146:147], v[152:153], v[146:147]
	v_pk_mul_f32 v[140:141], v[150:151], v[140:141]
	v_pk_mul_f32 v[54:55], v[54:55], v[146:147]
	v_cvt_f32_ubyte3_e32 v147, v137
	v_cvt_f32_ubyte2_e32 v146, v137
	v_rcp_f32_e32 v144, v144
	v_pk_mul_f32 v[52:53], v[52:53], v[140:141]
	v_cvt_f32_ubyte1_e32 v141, v137
	v_cvt_f32_ubyte0_e32 v140, v137
	v_pk_mul_f32 v[136:137], v[146:147], s[30:31] op_sel_hi:[1,0]
	v_pk_mul_f32 v[140:141], v[140:141], s[30:31] op_sel_hi:[1,0]
	v_pk_mul_f32 v[136:137], v[136:137], v[148:149]
	v_pk_mul_f32 v[140:141], v[140:141], v[144:145]
	v_pk_mul_f32 v[58:59], v[58:59], v[136:137]
	v_cvt_f32_ubyte1_e32 v136, v142
	v_mul_f32_e32 v137, 0x3b808081, v136
	v_cvt_f32_ubyte2_e32 v136, v142
	v_mul_f32_e32 v144, 0x3b808081, v136
	v_cvt_f32_ubyte3_e32 v136, v142
	v_mul_f32_e32 v145, 0x3b808081, v136
	v_cvt_f32_ubyte0_e32 v136, v143
	v_pk_mul_f32 v[56:57], v[56:57], v[140:141]
	v_mul_f32_e32 v140, 0x3b808081, v136
	v_cvt_f32_ubyte1_e32 v136, v143
	v_cvt_f32_ubyte0_e32 v16, v142
	v_mul_f32_e32 v141, 0x3b808081, v136
	v_cvt_f32_ubyte2_e32 v136, v143
	v_mul_f32_e32 v16, 0x3b808081, v16
	v_mul_f32_e32 v146, 0x3b808081, v136
	v_cvt_f32_ubyte3_e32 v136, v143
	v_mul_f32_e32 v150, 0x3b808081, v136
	v_rcp_f32_e32 v136, v16
	v_rcp_f32_e32 v137, v137
	v_rcp_f32_e32 v142, v144
	v_rcp_f32_e32 v144, v146
	v_rcp_f32_e32 v143, v145
	v_cvt_f32_ubyte1_e32 v147, v138
	v_cvt_f32_ubyte0_e32 v146, v138
	v_rcp_f32_e32 v140, v140
	v_rcp_f32_e32 v141, v141
	v_pk_mul_f32 v[146:147], v[146:147], s[30:31] op_sel_hi:[1,0]
	v_cvt_f32_ubyte3_e32 v149, v138
	v_cvt_f32_ubyte2_e32 v148, v138
	v_pk_mul_f32 v[136:137], v[146:147], v[136:137]
	v_pk_mul_f32 v[148:149], v[148:149], s[30:31] op_sel_hi:[1,0]
	v_pk_mul_f32 v[28:29], v[28:29], v[136:137]
	v_rcp_f32_e32 v145, v150
	v_cvt_f32_ubyte1_e32 v137, v139
	v_cvt_f32_ubyte0_e32 v136, v139
	v_pk_mul_f32 v[142:143], v[148:149], v[142:143]
	v_pk_mul_f32 v[136:137], v[136:137], s[30:31] op_sel_hi:[1,0]
	v_pk_mul_f32 v[30:31], v[30:31], v[142:143]
	v_cvt_f32_ubyte3_e32 v143, v139
	v_cvt_f32_ubyte2_e32 v142, v139
	v_pk_mul_f32 v[136:137], v[136:137], v[140:141]
	v_pk_mul_f32 v[138:139], v[142:143], s[30:31] op_sel_hi:[1,0]
	v_pk_mul_f32 v[32:33], v[32:33], v[136:137]
	v_cvt_f32_ubyte1_e32 v136, v134
	v_pk_mul_f32 v[138:139], v[138:139], v[144:145]
	v_cvt_f32_ubyte0_e32 v16, v134
	v_mul_f32_e32 v137, 0x3b808081, v136
	v_cvt_f32_ubyte2_e32 v136, v134
	v_cvt_f32_ubyte3_e32 v134, v134
	v_pk_mul_f32 v[34:35], v[34:35], v[138:139]
	v_mul_f32_e32 v139, 0x3b808081, v134
	v_cvt_f32_ubyte0_e32 v134, v135
	v_mul_f32_e32 v138, 0x3b808081, v136
	v_mul_f32_e32 v136, 0x3b808081, v134
	v_cvt_f32_ubyte1_e32 v134, v135
	v_mul_f32_e32 v140, 0x3b808081, v134
	v_cvt_f32_ubyte2_e32 v134, v135
	v_mul_f32_e32 v16, 0x3b808081, v16
	v_mul_f32_e32 v141, 0x3b808081, v134
	v_cvt_f32_ubyte3_e32 v134, v135
	v_rcp_f32_e32 v138, v138
	v_rcp_f32_e32 v139, v139
	v_mul_f32_e32 v146, 0x3b808081, v134
	v_rcp_f32_e32 v134, v16
	v_rcp_f32_e32 v135, v137
	v_cvt_f32_ubyte3_e32 v145, v18
	v_cvt_f32_ubyte2_e32 v144, v18
	v_rcp_f32_e32 v137, v140
	v_rcp_f32_e32 v140, v141
	v_cvt_f32_ubyte1_e32 v143, v18
	v_cvt_f32_ubyte0_e32 v142, v18
	v_pk_mul_f32 v[144:145], v[144:145], s[30:31] op_sel_hi:[1,0]
	v_rcp_f32_e32 v141, v146
	v_rcp_f32_e32 v136, v136
	v_pk_mul_f32 v[142:143], v[142:143], s[30:31] op_sel_hi:[1,0]
	v_pk_mul_f32 v[138:139], v[144:145], v[138:139]
	v_pk_mul_f32 v[134:135], v[142:143], v[134:135]
	v_pk_mul_f32 v[62:63], v[62:63], v[138:139]
	v_cvt_f32_ubyte3_e32 v139, v19
	v_cvt_f32_ubyte2_e32 v138, v19
	v_pk_mul_f32 v[60:61], v[60:61], v[134:135]
	v_cvt_f32_ubyte1_e32 v135, v19
	v_cvt_f32_ubyte0_e32 v134, v19
	v_pk_mul_f32 v[18:19], v[138:139], s[30:31] op_sel_hi:[1,0]
	v_pk_mul_f32 v[134:135], v[134:135], s[30:31] op_sel_hi:[1,0]
	v_pk_mul_f32 v[18:19], v[18:19], v[140:141]
	v_pk_mul_f32 v[134:135], v[134:135], v[136:137]
	v_pk_mul_f32 v[66:67], v[66:67], v[18:19]
	v_lshl_add_u64 v[18:19], v[132:133], 0, s[12:13]
	s_mov_b32 s12, 0x80000
	v_pk_mul_f32 v[64:65], v[64:65], v[134:135]
	v_add_co_u32_e32 v134, vcc, s12, v132
	s_mov_b64 s[12:13], 0x90000
	s_nop 0
	v_addc_co_u32_e32 v135, vcc, 0, v133, vcc
	v_mov_b32_e32 v148, v194
	v_mov_b32_e32 v149, v195
	v_mov_b32_e32 v154, v196
	v_mov_b32_e32 v155, v197
	v_mov_b32_e32 v142, v198
	v_mov_b32_e32 v143, v199
	v_mov_b32_e32 v156, v200
	v_mov_b32_e32 v157, v201
	v_lshl_add_u64 v[18:19], v[132:133], 0, s[12:13]
	s_mov_b32 s12, 0x90000
	v_add_co_u32_e32 v134, vcc, s12, v132
	s_mov_b64 s[12:13], 0xa0000
	s_nop 0
	v_addc_co_u32_e32 v135, vcc, 0, v133, vcc
	v_mov_b32_e32 v158, v202
	v_mov_b32_e32 v159, v203
	v_mov_b32_e32 v160, v204
	v_mov_b32_e32 v161, v205
	v_mov_b32_e32 v150, v206
	v_mov_b32_e32 v151, v207
	v_mov_b32_e32 v152, v208
	v_mov_b32_e32 v153, v209
	v_lshl_add_u64 v[18:19], v[132:133], 0, s[12:13]
	s_mov_b32 s12, 0xa0000
	v_add_co_u32_e32 v134, vcc, s12, v132
	s_mov_b64 s[12:13], 0xb0000
	s_nop 0
	v_addc_co_u32_e32 v135, vcc, 0, v133, vcc
	v_mov_b32_e32 v144, v210
	v_mov_b32_e32 v145, v211
	v_mov_b32_e32 v146, v212
	v_mov_b32_e32 v147, v213
	v_mov_b32_e32 v138, v214
	v_mov_b32_e32 v139, v215
	v_mov_b32_e32 v140, v216
	v_mov_b32_e32 v141, v217
	v_lshl_add_u64 v[162:163], v[132:133], 0, s[12:13]
	s_mov_b32 s12, 0xb0000
	v_add_co_u32_e32 v18, vcc, s12, v132
	s_waitcnt vmcnt(0)
	v_cvt_f32_ubyte3_e32 v189, v148
	v_addc_co_u32_e32 v19, vcc, 0, v133, vcc
	v_mov_b32_e32 v134, v218
	v_mov_b32_e32 v135, v219
	v_mov_b32_e32 v136, v220
	v_mov_b32_e32 v137, v221
	s_nop 0
	v_mov_b32_e32 v18, v222
	v_mov_b32_e32 v19, v223
	v_mov_b32_e32 v132, v224
	v_mov_b32_e32 v133, v225
	v_cvt_f32_ubyte1_e32 v162, v154
	v_cvt_f32_ubyte0_e32 v16, v154
	v_mul_f32_e32 v163, 0x3b808081, v162
	v_cvt_f32_ubyte2_e32 v162, v154
	v_cvt_f32_ubyte3_e32 v154, v154
	v_mul_f32_e32 v177, 0x3b808081, v154
	v_cvt_f32_ubyte0_e32 v154, v155
	v_mul_f32_e32 v176, 0x3b808081, v162
	v_mul_f32_e32 v162, 0x3b808081, v154
	v_cvt_f32_ubyte1_e32 v154, v155
	v_mul_f32_e32 v178, 0x3b808081, v154
	v_cvt_f32_ubyte2_e32 v154, v155
	v_mul_f32_e32 v16, 0x3b808081, v16
	v_mul_f32_e32 v179, 0x3b808081, v154
	v_cvt_f32_ubyte3_e32 v154, v155
	v_rcp_f32_e32 v176, v176
	v_rcp_f32_e32 v177, v177
	v_mul_f32_e32 v190, 0x3b808081, v154
	v_rcp_f32_e32 v154, v16
	v_rcp_f32_e32 v155, v163
	v_cvt_f32_ubyte2_e32 v188, v148
	v_rcp_f32_e32 v163, v178
	v_rcp_f32_e32 v178, v179
	v_cvt_f32_ubyte1_e32 v181, v148
	v_cvt_f32_ubyte0_e32 v180, v148
	v_pk_mul_f32 v[188:189], v[188:189], s[30:31] op_sel_hi:[1,0]
	v_rcp_f32_e32 v179, v190
	v_pk_mul_f32 v[180:181], v[180:181], s[30:31] op_sel_hi:[1,0]
	v_pk_mul_f32 v[176:177], v[188:189], v[176:177]
	v_pk_mul_f32 v[154:155], v[180:181], v[154:155]
	v_pk_mul_f32 v[70:71], v[70:71], v[176:177]
	v_cvt_f32_ubyte3_e32 v177, v149
	v_cvt_f32_ubyte2_e32 v176, v149
	v_rcp_f32_e32 v162, v162
	v_pk_mul_f32 v[68:69], v[68:69], v[154:155]
	v_cvt_f32_ubyte1_e32 v155, v149
	v_cvt_f32_ubyte0_e32 v154, v149
	v_pk_mul_f32 v[148:149], v[176:177], s[30:31] op_sel_hi:[1,0]
	v_pk_mul_f32 v[154:155], v[154:155], s[30:31] op_sel_hi:[1,0]
	v_pk_mul_f32 v[148:149], v[148:149], v[178:179]
	v_pk_mul_f32 v[154:155], v[154:155], v[162:163]
	v_pk_mul_f32 v[74:75], v[74:75], v[148:149]
	v_cvt_f32_ubyte1_e32 v148, v156
	v_mul_f32_e32 v149, 0x3b808081, v148
	v_cvt_f32_ubyte2_e32 v148, v156
	v_mul_f32_e32 v162, 0x3b808081, v148
	v_cvt_f32_ubyte3_e32 v148, v156
	v_mul_f32_e32 v163, 0x3b808081, v148
	v_cvt_f32_ubyte0_e32 v148, v157
	v_pk_mul_f32 v[72:73], v[72:73], v[154:155]
	v_mul_f32_e32 v154, 0x3b808081, v148
	v_cvt_f32_ubyte1_e32 v148, v157
	v_cvt_f32_ubyte0_e32 v16, v156
	v_mul_f32_e32 v155, 0x3b808081, v148
	v_cvt_f32_ubyte2_e32 v148, v157
	v_mul_f32_e32 v16, 0x3b808081, v16
	v_mul_f32_e32 v176, 0x3b808081, v148
	v_cvt_f32_ubyte3_e32 v148, v157
	v_rcp_f32_e32 v156, v162
	v_rcp_f32_e32 v157, v163
	v_mul_f32_e32 v180, 0x3b808081, v148
	v_rcp_f32_e32 v148, v16
	v_rcp_f32_e32 v149, v149
	v_cvt_f32_ubyte3_e32 v179, v142
	v_cvt_f32_ubyte2_e32 v178, v142
	v_rcp_f32_e32 v162, v176
	v_cvt_f32_ubyte1_e32 v177, v142
	v_cvt_f32_ubyte0_e32 v176, v142
	v_pk_mul_f32 v[178:179], v[178:179], s[30:31] op_sel_hi:[1,0]
	v_rcp_f32_e32 v163, v180
	v_pk_mul_f32 v[176:177], v[176:177], s[30:31] op_sel_hi:[1,0]
	v_pk_mul_f32 v[156:157], v[178:179], v[156:157]
	v_pk_mul_f32 v[148:149], v[176:177], v[148:149]
	v_pk_mul_f32 v[102:103], v[102:103], v[156:157]
	v_cvt_f32_ubyte3_e32 v157, v143
	v_cvt_f32_ubyte2_e32 v156, v143
	v_rcp_f32_e32 v154, v154
	v_rcp_f32_e32 v155, v155
	v_pk_mul_f32 v[100:101], v[100:101], v[148:149]
	v_cvt_f32_ubyte1_e32 v149, v143
	v_cvt_f32_ubyte0_e32 v148, v143
	v_pk_mul_f32 v[142:143], v[156:157], s[30:31] op_sel_hi:[1,0]
	v_pk_mul_f32 v[148:149], v[148:149], s[30:31] op_sel_hi:[1,0]
	v_pk_mul_f32 v[142:143], v[142:143], v[162:163]
	v_pk_mul_f32 v[148:149], v[148:149], v[154:155]
	v_pk_mul_f32 v[106:107], v[106:107], v[142:143]
	v_cvt_f32_ubyte1_e32 v142, v160
	v_mul_f32_e32 v143, 0x3b808081, v142
	v_cvt_f32_ubyte2_e32 v142, v160
	v_mul_f32_e32 v154, 0x3b808081, v142
	v_cvt_f32_ubyte3_e32 v142, v160
	v_mul_f32_e32 v155, 0x3b808081, v142
	v_cvt_f32_ubyte0_e32 v142, v161
	v_pk_mul_f32 v[104:105], v[104:105], v[148:149]
	v_mul_f32_e32 v148, 0x3b808081, v142
	v_cvt_f32_ubyte1_e32 v142, v161
	v_cvt_f32_ubyte0_e32 v16, v160
	v_mul_f32_e32 v149, 0x3b808081, v142
	v_cvt_f32_ubyte2_e32 v142, v161
	v_mul_f32_e32 v16, 0x3b808081, v16
	v_mul_f32_e32 v156, 0x3b808081, v142
	v_cvt_f32_ubyte3_e32 v142, v161
	v_mul_f32_e32 v157, 0x3b808081, v142
	v_rcp_f32_e32 v142, v16
	v_rcp_f32_e32 v143, v143
	v_cvt_f32_ubyte1_e32 v161, v158
	v_cvt_f32_ubyte0_e32 v160, v158
	v_rcp_f32_e32 v148, v148
	v_rcp_f32_e32 v149, v149
	v_rcp_f32_e32 v154, v154
	v_rcp_f32_e32 v155, v155
	v_pk_mul_f32 v[160:161], v[160:161], s[30:31] op_sel_hi:[1,0]
	v_cvt_f32_ubyte3_e32 v163, v158
	v_pk_mul_f32 v[142:143], v[160:161], v[142:143]
	v_cvt_f32_ubyte2_e32 v162, v158
	v_pk_mul_f32 v[76:77], v[76:77], v[142:143]
	v_cvt_f32_ubyte1_e32 v143, v159
	v_cvt_f32_ubyte0_e32 v142, v159
	v_rcp_f32_e32 v156, v156
	v_pk_mul_f32 v[162:163], v[162:163], s[30:31] op_sel_hi:[1,0]
	v_rcp_f32_e32 v157, v157
	v_pk_mul_f32 v[142:143], v[142:143], s[30:31] op_sel_hi:[1,0]
	v_pk_mul_f32 v[154:155], v[162:163], v[154:155]
	v_pk_mul_f32 v[142:143], v[142:143], v[148:149]
	v_pk_mul_f32 v[78:79], v[78:79], v[154:155]
	v_cvt_f32_ubyte3_e32 v155, v159
	v_cvt_f32_ubyte2_e32 v154, v159
	v_pk_mul_f32 v[80:81], v[80:81], v[142:143]
	v_cvt_f32_ubyte1_e32 v142, v152
	v_pk_mul_f32 v[154:155], v[154:155], s[30:31] op_sel_hi:[1,0]
	v_mul_f32_e32 v143, 0x3b808081, v142
	v_cvt_f32_ubyte2_e32 v142, v152
	v_pk_mul_f32 v[148:149], v[154:155], v[156:157]
	v_mul_f32_e32 v154, 0x3b808081, v142
	v_cvt_f32_ubyte3_e32 v142, v152
	v_mul_f32_e32 v155, 0x3b808081, v142
	v_cvt_f32_ubyte0_e32 v142, v153
	v_pk_mul_f32 v[82:83], v[82:83], v[148:149]
	v_mul_f32_e32 v148, 0x3b808081, v142
	v_cvt_f32_ubyte1_e32 v142, v153
	v_cvt_f32_ubyte0_e32 v16, v152
	v_mul_f32_e32 v149, 0x3b808081, v142
	v_cvt_f32_ubyte2_e32 v142, v153
	v_mul_f32_e32 v16, 0x3b808081, v16
	v_mul_f32_e32 v156, 0x3b808081, v142
	v_cvt_f32_ubyte3_e32 v142, v153
	v_mul_f32_e32 v160, 0x3b808081, v142
	v_rcp_f32_e32 v142, v16
	v_rcp_f32_e32 v143, v143
	v_rcp_f32_e32 v152, v154
	v_rcp_f32_e32 v154, v156
	v_rcp_f32_e32 v153, v155
	v_cvt_f32_ubyte1_e32 v157, v150
	v_cvt_f32_ubyte0_e32 v156, v150
	v_rcp_f32_e32 v148, v148
	v_rcp_f32_e32 v149, v149
	v_pk_mul_f32 v[156:157], v[156:157], s[30:31] op_sel_hi:[1,0]
	v_cvt_f32_ubyte3_e32 v159, v150
	v_cvt_f32_ubyte2_e32 v158, v150
	v_pk_mul_f32 v[142:143], v[156:157], v[142:143]
	v_pk_mul_f32 v[158:159], v[158:159], s[30:31] op_sel_hi:[1,0]
	v_pk_mul_f32 v[108:109], v[108:109], v[142:143]
	v_rcp_f32_e32 v155, v160
	v_cvt_f32_ubyte1_e32 v143, v151
	v_cvt_f32_ubyte0_e32 v142, v151
	v_pk_mul_f32 v[152:153], v[158:159], v[152:153]
	v_pk_mul_f32 v[142:143], v[142:143], s[30:31] op_sel_hi:[1,0]
	v_pk_mul_f32 v[110:111], v[110:111], v[152:153]
	v_cvt_f32_ubyte3_e32 v153, v151
	v_cvt_f32_ubyte2_e32 v152, v151
	v_pk_mul_f32 v[142:143], v[142:143], v[148:149]
	v_pk_mul_f32 v[150:151], v[152:153], s[30:31] op_sel_hi:[1,0]
	v_pk_mul_f32 v[112:113], v[112:113], v[142:143]
	v_cvt_f32_ubyte1_e32 v142, v146
	v_pk_mul_f32 v[148:149], v[150:151], v[154:155]
	v_mul_f32_e32 v143, 0x3b808081, v142
	v_cvt_f32_ubyte2_e32 v142, v146
	v_pk_mul_f32 v[114:115], v[114:115], v[148:149]
	v_mul_f32_e32 v148, 0x3b808081, v142
	v_cvt_f32_ubyte3_e32 v142, v146
	v_mul_f32_e32 v149, 0x3b808081, v142
	v_cvt_f32_ubyte0_e32 v142, v147
	v_cvt_f32_ubyte0_e32 v16, v146
	v_mul_f32_e32 v146, 0x3b808081, v142
	v_cvt_f32_ubyte1_e32 v142, v147
	v_mul_f32_e32 v150, 0x3b808081, v142
	v_cvt_f32_ubyte2_e32 v142, v147
	v_mul_f32_e32 v16, 0x3b808081, v16
	v_mul_f32_e32 v151, 0x3b808081, v142
	v_cvt_f32_ubyte3_e32 v142, v147
	v_mul_f32_e32 v156, 0x3b808081, v142
	v_rcp_f32_e32 v142, v16
	v_rcp_f32_e32 v143, v143
	v_rcp_f32_e32 v148, v148
	v_rcp_f32_e32 v149, v149
	v_cvt_f32_ubyte1_e32 v153, v144
	v_cvt_f32_ubyte0_e32 v152, v144
	v_rcp_f32_e32 v146, v146
	v_rcp_f32_e32 v147, v150
	v_pk_mul_f32 v[152:153], v[152:153], s[30:31] op_sel_hi:[1,0]
	v_cvt_f32_ubyte3_e32 v155, v144
	v_cvt_f32_ubyte2_e32 v154, v144
	v_pk_mul_f32 v[142:143], v[152:153], v[142:143]
	v_rcp_f32_e32 v150, v151
	v_pk_mul_f32 v[154:155], v[154:155], s[30:31] op_sel_hi:[1,0]
	v_pk_mul_f32 v[84:85], v[84:85], v[142:143]
	v_rcp_f32_e32 v151, v156
	v_cvt_f32_ubyte1_e32 v143, v145
	v_cvt_f32_ubyte0_e32 v142, v145
	v_pk_mul_f32 v[148:149], v[154:155], v[148:149]
	v_pk_mul_f32 v[142:143], v[142:143], s[30:31] op_sel_hi:[1,0]
	v_pk_mul_f32 v[86:87], v[86:87], v[148:149]
	v_cvt_f32_ubyte3_e32 v149, v145
	v_cvt_f32_ubyte2_e32 v148, v145
	v_pk_mul_f32 v[142:143], v[142:143], v[146:147]
	v_pk_mul_f32 v[144:145], v[148:149], s[30:31] op_sel_hi:[1,0]
	v_pk_mul_f32 v[88:89], v[88:89], v[142:143]
	v_cvt_f32_ubyte1_e32 v142, v140
	v_pk_mul_f32 v[144:145], v[144:145], v[150:151]
	v_cvt_f32_ubyte0_e32 v16, v140
	v_mul_f32_e32 v143, 0x3b808081, v142
	v_cvt_f32_ubyte2_e32 v142, v140
	v_cvt_f32_ubyte3_e32 v140, v140
	v_pk_mul_f32 v[90:91], v[90:91], v[144:145]
	v_mul_f32_e32 v145, 0x3b808081, v140
	v_cvt_f32_ubyte0_e32 v140, v141
	v_mul_f32_e32 v144, 0x3b808081, v142
	v_mul_f32_e32 v142, 0x3b808081, v140
	v_cvt_f32_ubyte1_e32 v140, v141
	v_mul_f32_e32 v146, 0x3b808081, v140
	v_cvt_f32_ubyte2_e32 v140, v141
	v_mul_f32_e32 v16, 0x3b808081, v16
	v_mul_f32_e32 v147, 0x3b808081, v140
	v_cvt_f32_ubyte3_e32 v140, v141
	v_rcp_f32_e32 v144, v144
	v_rcp_f32_e32 v145, v145
	v_mul_f32_e32 v152, 0x3b808081, v140
	v_rcp_f32_e32 v140, v16
	v_rcp_f32_e32 v141, v143
	v_cvt_f32_ubyte3_e32 v151, v138
	v_cvt_f32_ubyte2_e32 v150, v138
	v_rcp_f32_e32 v143, v146
	v_rcp_f32_e32 v146, v147
	v_cvt_f32_ubyte1_e32 v149, v138
	v_cvt_f32_ubyte0_e32 v148, v138
	v_pk_mul_f32 v[150:151], v[150:151], s[30:31] op_sel_hi:[1,0]
	v_rcp_f32_e32 v147, v152
	v_pk_mul_f32 v[148:149], v[148:149], s[30:31] op_sel_hi:[1,0]
	v_pk_mul_f32 v[144:145], v[150:151], v[144:145]
	v_rcp_f32_e32 v142, v142
	v_pk_mul_f32 v[140:141], v[148:149], v[140:141]
	v_pk_mul_f32 v[118:119], v[118:119], v[144:145]
	v_cvt_f32_ubyte3_e32 v145, v139
	v_cvt_f32_ubyte2_e32 v144, v139
	v_pk_mul_f32 v[116:117], v[116:117], v[140:141]
	v_cvt_f32_ubyte1_e32 v141, v139
	v_cvt_f32_ubyte0_e32 v140, v139
	v_pk_mul_f32 v[138:139], v[144:145], s[30:31] op_sel_hi:[1,0]
	v_pk_mul_f32 v[140:141], v[140:141], s[30:31] op_sel_hi:[1,0]
	v_pk_mul_f32 v[138:139], v[138:139], v[146:147]
	v_pk_mul_f32 v[140:141], v[140:141], v[142:143]
	v_pk_mul_f32 v[122:123], v[122:123], v[138:139]
	s_waitcnt vmcnt(0)
	v_cvt_f32_ubyte1_e32 v138, v136
	v_cvt_f32_ubyte0_e32 v16, v136
	v_mul_f32_e32 v139, 0x3b808081, v138
	v_cvt_f32_ubyte2_e32 v138, v136
	v_cvt_f32_ubyte3_e32 v136, v136
	v_pk_mul_f32 v[120:121], v[120:121], v[140:141]
	v_mul_f32_e32 v141, 0x3b808081, v136
	v_cvt_f32_ubyte0_e32 v136, v137
	v_mul_f32_e32 v140, 0x3b808081, v138
	v_mul_f32_e32 v138, 0x3b808081, v136
	v_cvt_f32_ubyte1_e32 v136, v137
	v_mul_f32_e32 v142, 0x3b808081, v136
	v_cvt_f32_ubyte2_e32 v136, v137
	v_mul_f32_e32 v16, 0x3b808081, v16
	v_mul_f32_e32 v143, 0x3b808081, v136
	v_cvt_f32_ubyte3_e32 v136, v137
	v_rcp_f32_e32 v140, v140
	v_rcp_f32_e32 v141, v141
	v_mul_f32_e32 v148, 0x3b808081, v136
	v_rcp_f32_e32 v136, v16
	v_rcp_f32_e32 v137, v139
	v_cvt_f32_ubyte3_e32 v147, v134
	v_cvt_f32_ubyte2_e32 v146, v134
	v_rcp_f32_e32 v139, v142
	v_rcp_f32_e32 v142, v143
	v_cvt_f32_ubyte1_e32 v145, v134
	v_cvt_f32_ubyte0_e32 v144, v134
	v_pk_mul_f32 v[146:147], v[146:147], s[30:31] op_sel_hi:[1,0]
	v_rcp_f32_e32 v143, v148
	v_pk_mul_f32 v[144:145], v[144:145], s[30:31] op_sel_hi:[1,0]
	v_pk_mul_f32 v[140:141], v[146:147], v[140:141]
	v_rcp_f32_e32 v138, v138
	v_pk_mul_f32 v[136:137], v[144:145], v[136:137]
	v_pk_mul_f32 v[94:95], v[94:95], v[140:141]
	v_cvt_f32_ubyte3_e32 v141, v135
	v_cvt_f32_ubyte2_e32 v140, v135
	v_pk_mul_f32 v[92:93], v[92:93], v[136:137]
	v_cvt_f32_ubyte1_e32 v137, v135
	v_cvt_f32_ubyte0_e32 v136, v135
	v_pk_mul_f32 v[134:135], v[140:141], s[30:31] op_sel_hi:[1,0]
	v_pk_mul_f32 v[136:137], v[136:137], s[30:31] op_sel_hi:[1,0]
	v_pk_mul_f32 v[134:135], v[134:135], v[142:143]
	v_pk_mul_f32 v[136:137], v[136:137], v[138:139]
	v_pk_mul_f32 v[98:99], v[98:99], v[134:135]
	v_cvt_f32_ubyte1_e32 v134, v132
	v_cvt_f32_ubyte0_e32 v16, v132
	v_mul_f32_e32 v135, 0x3b808081, v134
	v_cvt_f32_ubyte2_e32 v134, v132
	v_cvt_f32_ubyte3_e32 v132, v132
	v_pk_mul_f32 v[96:97], v[96:97], v[136:137]
	v_mul_f32_e32 v137, 0x3b808081, v132
	v_cvt_f32_ubyte0_e32 v132, v133
	v_mul_f32_e32 v136, 0x3b808081, v134
	v_mul_f32_e32 v134, 0x3b808081, v132
	v_cvt_f32_ubyte1_e32 v132, v133
	v_mul_f32_e32 v138, 0x3b808081, v132
	v_cvt_f32_ubyte2_e32 v132, v133
	v_mul_f32_e32 v16, 0x3b808081, v16
	v_mul_f32_e32 v139, 0x3b808081, v132
	v_cvt_f32_ubyte3_e32 v132, v133
	v_mul_f32_e32 v144, 0x3b808081, v132
	v_rcp_f32_e32 v132, v16
	v_rcp_f32_e32 v133, v135
	v_rcp_f32_e32 v136, v136
	v_rcp_f32_e32 v137, v137
	v_cvt_f32_ubyte1_e32 v141, v18
	v_cvt_f32_ubyte0_e32 v140, v18
	v_cvt_f32_ubyte3_e32 v143, v18
	v_cvt_f32_ubyte2_e32 v142, v18
	v_rcp_f32_e32 v134, v134
	v_rcp_f32_e32 v135, v138
	v_rcp_f32_e32 v138, v139
	v_pk_mul_f32 v[142:143], v[142:143], s[30:31] op_sel_hi:[1,0]
	v_pk_mul_f32 v[140:141], v[140:141], s[30:31] op_sel_hi:[1,0]
	v_rcp_f32_e32 v139, v144
	v_pk_mul_f32 v[132:133], v[140:141], v[132:133]
	v_pk_mul_f32 v[136:137], v[142:143], v[136:137]
	v_pk_mul_f32 v[124:125], v[124:125], v[132:133]
	v_pk_mul_f32 v[126:127], v[126:127], v[136:137]
	v_cvt_f32_ubyte1_e32 v133, v19
	v_cvt_f32_ubyte0_e32 v132, v19
	v_cvt_f32_ubyte3_e32 v137, v19
	v_cvt_f32_ubyte2_e32 v136, v19
	v_pk_mul_f32 v[18:19], v[136:137], s[30:31] op_sel_hi:[1,0]
	v_pk_mul_f32 v[132:133], v[132:133], s[30:31] op_sel_hi:[1,0]
	v_pk_mul_f32 v[18:19], v[18:19], v[138:139]
	v_pk_mul_f32 v[132:133], v[132:133], v[134:135]
	v_pk_mul_f32 v[130:131], v[130:131], v[18:19]
	v_pk_mul_f32 v[128:129], v[128:129], v[132:133]
	s_mov_b64 s[12:13], -1
	s_and_b64 vcc, exec, s[8:9]
	s_cbranch_vccz .LBB0_1164
